# ffn1 as 192x256 tiles: all 8 waves compute and share the LDS-DMA issue, K-slices of 64 in two 56 KiB stages with early release (fragments to registers, second barrier frees the stage for slice k+2)
# speedup vs baseline: 1.1036x; 1.0093x over previous
.Lgm_f1_entry:
	s_waitcnt vmcnt(0) lgkmcnt(0)
	s_mov_b64 exec, -1
	s_add_u32 s56, s96, 0x3a24000
	s_addc_u32 s57, s97, 0
	s_mov_b32 s52, s61
	s_mov_b32 s53, s63
	s_movk_i32 s54, 0x200
	s_cmp_ge_u32 s53, s54
	s_cbranch_scc1 .Lgm_f1_exit
	s_mov_b32 s30, 0
	s_mov_b32 s4, s53
.Lgm_f1_cnt:
	s_add_u32 s30, s30, 16
	s_add_u32 s4, s4, s52
	s_cmp_lt_u32 s4, s54
	s_cbranch_scc1 .Lgm_f1_cnt
	s_add_u32 s48, s96, 0x2e24000
	s_addc_u32 s49, s97, 0
	s_mul_i32 s4, s36, 0x800000
	s_add_u32 s50, s96, 0xd80000
	s_addc_u32 s51, s97, 0
	s_add_u32 s50, s50, s4
	s_addc_u32 s51, s51, 0
	v_and_b32_e32 v0, 63, v206
	v_lshrrev_b32_e32 v1, 6, v206
	s_nop 1
	v_readfirstlane_b32 s42, v1
	v_lshrrev_b32_e32 v3, 3, v0
	v_and_b32_e32 v226, 7, v0
	v_xor_b32_e32 v226, v226, v3
	v_lshl_add_u32 v3, v1, 3, v3
	v_lshlrev_b32_e32 v3, 11, v3
	v_lshl_add_u32 v222, v226, 4, v3
	v_add_u32_e32 v223, 0x20000, v222
	v_add_u32_e32 v224, 0x40000, v222
	v_add_u32_e32 v225, 0x60000, v222
	v_and_b32_e32 v194, 15, v0
	v_lshrrev_b32_e32 v195, 4, v0
	v_and_b32_e32 v3, 7, v194
	v_xor_b32_e32 v3, v3, v195
	v_lshlrev_b32_e32 v3, 4, v3
	v_lshrrev_b32_e32 v228, 2, v1
	v_and_b32_e32 v229, 3, v1
	v_mul_u32_u24_e32 v230, 96, v228
	v_add_u32_e32 v231, v230, v194
	v_lshl_add_u32 v199, v231, 7, v3
	v_xor_b32_e32 v200, 64, v199
	v_lshl_add_u32 v231, v229, 6, v194
	v_lshl_add_u32 v201, v231, 7, v3
	v_add_u32_e32 v201, 0x6000, v201
	v_xor_b32_e32 v202, 64, v201
	s_mul_i32 s5, s42, 4352
	s_mov_b32 s6, 0x1ec10
	s_cmp_lt_u32 s42, 4
	s_cselect_b32 s6, 0x1e000, s6
	s_add_u32 s5, s5, s6
	v_mul_u32_u24_e32 v3, 1088, v195
	v_lshl_add_u32 v3, v194, 2, v3
	v_add_u32_e32 v203, s5, v3
	v_mul_u32_u24_e32 v3, 272, v195
	v_lshl_add_u32 v3, v194, 4, v3
	v_add_u32_e32 v204, s5, v3
	v_add_u32_e32 v190, v230, v195
	v_lshlrev_b32_e32 v3, 6, v229
	v_lshl_add_u32 v3, v194, 2, v3
	s_mov_b32 s4, 0x2000
	v_mul_lo_u32 v205, v190, s4
	v_lshl_add_u32 v205, v3, 1, v205
	v_lshlrev_b32_e32 v191, 2, v3
	v_mov_b32_e32 v193, v3
	s_lshl_b32 s42, s42, 10
	v_mov_b32_e32 v4, 0
	v_mov_b32_e32 v5, 0
	v_mov_b32_e32 v6, 0
	v_mov_b32_e32 v7, 0
	v_mov_b32_e32 v8, 0
	v_mov_b32_e32 v9, 0
	v_mov_b32_e32 v10, 0
	v_mov_b32_e32 v11, 0
	v_mov_b32_e32 v12, 0
	v_mov_b32_e32 v13, 0
	v_mov_b32_e32 v14, 0
	v_mov_b32_e32 v15, 0
	v_mov_b32_e32 v16, 0
	v_mov_b32_e32 v17, 0
	v_mov_b32_e32 v18, 0
	v_mov_b32_e32 v19, 0
	v_mov_b32_e32 v20, 0
	v_mov_b32_e32 v21, 0
	v_mov_b32_e32 v22, 0
	v_mov_b32_e32 v23, 0
	v_mov_b32_e32 v24, 0
	v_mov_b32_e32 v25, 0
	v_mov_b32_e32 v26, 0
	v_mov_b32_e32 v27, 0
	v_mov_b32_e32 v28, 0
	v_mov_b32_e32 v29, 0
	v_mov_b32_e32 v30, 0
	v_mov_b32_e32 v31, 0
	v_mov_b32_e32 v32, 0
	v_mov_b32_e32 v33, 0
	v_mov_b32_e32 v34, 0
	v_mov_b32_e32 v35, 0
	v_mov_b32_e32 v36, 0
	v_mov_b32_e32 v37, 0
	v_mov_b32_e32 v38, 0
	v_mov_b32_e32 v39, 0
	v_mov_b32_e32 v40, 0
	v_mov_b32_e32 v41, 0
	v_mov_b32_e32 v42, 0
	v_mov_b32_e32 v43, 0
	v_mov_b32_e32 v44, 0
	v_mov_b32_e32 v45, 0
	v_mov_b32_e32 v46, 0
	v_mov_b32_e32 v47, 0
	v_mov_b32_e32 v48, 0
	v_mov_b32_e32 v49, 0
	v_mov_b32_e32 v50, 0
	v_mov_b32_e32 v51, 0
	v_mov_b32_e32 v52, 0
	v_mov_b32_e32 v53, 0
	v_mov_b32_e32 v54, 0
	v_mov_b32_e32 v55, 0
	v_mov_b32_e32 v56, 0
	v_mov_b32_e32 v57, 0
	v_mov_b32_e32 v58, 0
	v_mov_b32_e32 v59, 0
	v_mov_b32_e32 v60, 0
	v_mov_b32_e32 v61, 0
	v_mov_b32_e32 v62, 0
	v_mov_b32_e32 v63, 0
	v_mov_b32_e32 v64, 0
	v_mov_b32_e32 v65, 0
	v_mov_b32_e32 v66, 0
	v_mov_b32_e32 v67, 0
	v_mov_b32_e32 v68, 0
	v_mov_b32_e32 v69, 0
	v_mov_b32_e32 v70, 0
	v_mov_b32_e32 v71, 0
	v_mov_b32_e32 v72, 0
	v_mov_b32_e32 v73, 0
	v_mov_b32_e32 v74, 0
	v_mov_b32_e32 v75, 0
	v_mov_b32_e32 v76, 0
	v_mov_b32_e32 v77, 0
	v_mov_b32_e32 v78, 0
	v_mov_b32_e32 v79, 0
	v_mov_b32_e32 v80, 0
	v_mov_b32_e32 v81, 0
	v_mov_b32_e32 v82, 0
	v_mov_b32_e32 v83, 0
	v_mov_b32_e32 v84, 0
	v_mov_b32_e32 v85, 0
	v_mov_b32_e32 v86, 0
	v_mov_b32_e32 v87, 0
	v_mov_b32_e32 v88, 0
	v_mov_b32_e32 v89, 0
	v_mov_b32_e32 v90, 0
	v_mov_b32_e32 v91, 0
	v_mov_b32_e32 v92, 0
	v_mov_b32_e32 v93, 0
	v_mov_b32_e32 v94, 0
	v_mov_b32_e32 v95, 0
	v_mov_b32_e32 v96, 0
	v_mov_b32_e32 v97, 0
	v_mov_b32_e32 v98, 0
	v_mov_b32_e32 v99, 0
	s_mov_b32 s31, 0
	s_mov_b32 s34, 0
	s_mov_b32 s35, s53
	s_mov_b32 s38, s53
	s_mov_b32 s39, 0
	s_mov_b32 s40, 0
	s_and_b32 s4, s38, 31
	s_mul_i32 s4, s4, 0x60000
	s_add_u32 s44, s48, s4
	s_addc_u32 s45, s49, 0
	s_lshr_b32 s4, s38, 5
	s_mul_i32 s4, s4, 0x80000
	s_add_u32 s46, s50, s4
	s_addc_u32 s47, s51, 0
	s_add_u32 s41, s42, 0x0
	s_add_u32 m0, s41, 0x0
	s_nop 0
	global_load_lds_dwordx4 v222, s[44:45]
	s_add_u32 m0, s41, 0x2000
	s_nop 0
	global_load_lds_dwordx4 v223, s[44:45]
	s_add_u32 m0, s41, 0x4000
	s_nop 0
	global_load_lds_dwordx4 v224, s[44:45]
	s_add_u32 m0, s41, 0x6000
	s_nop 0
	global_load_lds_dwordx4 v222, s[46:47]
	s_add_u32 m0, s41, 0x8000
	s_nop 0
	global_load_lds_dwordx4 v223, s[46:47]
	s_add_u32 m0, s41, 0xa000
	s_nop 0
	global_load_lds_dwordx4 v224, s[46:47]
	s_add_u32 m0, s41, 0xc000
	s_nop 0
	global_load_lds_dwordx4 v225, s[46:47]
.Lgm_f1_dsk1:
	s_add_u32 s39, s39, 1
	s_add_u32 s44, s44, 0x80
	s_addc_u32 s45, s45, 0
	s_add_u32 s46, s46, 0x80
	s_addc_u32 s47, s47, 0
	s_cmp_lt_u32 s39, 16
	s_cbranch_scc1 .Lgm_f1_dadv2
	s_mov_b32 s39, 0
	s_add_u32 s4, s38, s52
	s_cmp_lt_u32 s4, s54
	s_cselect_b32 s38, s4, s38
	s_and_b32 s4, s38, 31
	s_mul_i32 s4, s4, 0x60000
	s_add_u32 s44, s48, s4
	s_addc_u32 s45, s49, 0
	s_lshr_b32 s4, s38, 5
	s_mul_i32 s4, s4, 0x80000
	s_add_u32 s46, s50, s4
	s_addc_u32 s47, s51, 0
.Lgm_f1_dadv2:
	s_add_u32 s41, s42, 0xe000
	s_add_u32 m0, s41, 0x0
	s_nop 0
	global_load_lds_dwordx4 v222, s[44:45]
	s_add_u32 m0, s41, 0x2000
	s_nop 0
	global_load_lds_dwordx4 v223, s[44:45]
	s_add_u32 m0, s41, 0x4000
	s_nop 0
	global_load_lds_dwordx4 v224, s[44:45]
	s_add_u32 m0, s41, 0x6000
	s_nop 0
	global_load_lds_dwordx4 v222, s[46:47]
	s_add_u32 m0, s41, 0x8000
	s_nop 0
	global_load_lds_dwordx4 v223, s[46:47]
	s_add_u32 m0, s41, 0xa000
	s_nop 0
	global_load_lds_dwordx4 v224, s[46:47]
	s_add_u32 m0, s41, 0xc000
	s_nop 0
	global_load_lds_dwordx4 v225, s[46:47]

.Lgm_f1_dadv4:
	s_waitcnt vmcnt(7)
.Lgm_f1_loop:
	s_barrier
	ds_read_b128 v[100:103], v199 offset:0
	ds_read_b128 v[104:107], v199 offset:2048
	ds_read_b128 v[108:111], v199 offset:4096
	ds_read_b128 v[112:115], v199 offset:6144
	ds_read_b128 v[116:119], v199 offset:8192
	ds_read_b128 v[120:123], v199 offset:10240
	ds_read_b128 v[124:127], v201 offset:0
	ds_read_b128 v[128:131], v201 offset:2048
	ds_read_b128 v[132:135], v201 offset:4096
	ds_read_b128 v[136:139], v201 offset:6144
	ds_read_b128 v[140:143], v200 offset:0
	ds_read_b128 v[144:147], v200 offset:2048
	ds_read_b128 v[148:151], v200 offset:4096
	ds_read_b128 v[152:155], v200 offset:6144
	ds_read_b128 v[156:159], v200 offset:8192
	s_waitcnt lgkmcnt(5)
	ds_read_b128 v[160:163], v200 offset:10240
	ds_read_b128 v[164:167], v202 offset:0
	ds_read_b128 v[168:171], v202 offset:2048
	ds_read_b128 v[172:175], v202 offset:4096
	ds_read_b128 v[176:179], v202 offset:6144
	v_mfma_f32_16x16x32_bf16 v[4:7], v[100:103], v[124:127], v[4:7]
	v_mfma_f32_16x16x32_bf16 v[20:23], v[104:107], v[124:127], v[20:23]
	v_mfma_f32_16x16x32_bf16 v[36:39], v[108:111], v[124:127], v[36:39]
	v_mfma_f32_16x16x32_bf16 v[52:55], v[112:115], v[124:127], v[52:55]
	v_mfma_f32_16x16x32_bf16 v[68:71], v[116:119], v[124:127], v[68:71]
	v_mfma_f32_16x16x32_bf16 v[84:87], v[120:123], v[124:127], v[84:87]
	v_mfma_f32_16x16x32_bf16 v[8:11], v[100:103], v[128:131], v[8:11]
	v_mfma_f32_16x16x32_bf16 v[24:27], v[104:107], v[128:131], v[24:27]
	v_mfma_f32_16x16x32_bf16 v[40:43], v[108:111], v[128:131], v[40:43]
	v_mfma_f32_16x16x32_bf16 v[56:59], v[112:115], v[128:131], v[56:59]
	v_mfma_f32_16x16x32_bf16 v[72:75], v[116:119], v[128:131], v[72:75]
	v_mfma_f32_16x16x32_bf16 v[88:91], v[120:123], v[128:131], v[88:91]
	v_mfma_f32_16x16x32_bf16 v[12:15], v[100:103], v[132:135], v[12:15]
	v_mfma_f32_16x16x32_bf16 v[28:31], v[104:107], v[132:135], v[28:31]
	v_mfma_f32_16x16x32_bf16 v[44:47], v[108:111], v[132:135], v[44:47]
	v_mfma_f32_16x16x32_bf16 v[60:63], v[112:115], v[132:135], v[60:63]
	v_mfma_f32_16x16x32_bf16 v[76:79], v[116:119], v[132:135], v[76:79]
	v_mfma_f32_16x16x32_bf16 v[92:95], v[120:123], v[132:135], v[92:95]
	v_mfma_f32_16x16x32_bf16 v[16:19], v[100:103], v[136:139], v[16:19]
	v_mfma_f32_16x16x32_bf16 v[32:35], v[104:107], v[136:139], v[32:35]
	v_mfma_f32_16x16x32_bf16 v[48:51], v[108:111], v[136:139], v[48:51]
	v_mfma_f32_16x16x32_bf16 v[64:67], v[112:115], v[136:139], v[64:67]
	v_mfma_f32_16x16x32_bf16 v[80:83], v[116:119], v[136:139], v[80:83]
	v_mfma_f32_16x16x32_bf16 v[96:99], v[120:123], v[136:139], v[96:99]
	s_waitcnt lgkmcnt(0)
	s_barrier
	s_add_u32 s41, s42, s40
	v_mfma_f32_16x16x32_bf16 v[4:7], v[140:143], v[164:167], v[4:7]
	s_add_u32 m0, s41, 0x0
	v_mfma_f32_16x16x32_bf16 v[20:23], v[144:147], v[164:167], v[20:23]
	global_load_lds_dwordx4 v222, s[44:45]
	v_mfma_f32_16x16x32_bf16 v[36:39], v[148:151], v[164:167], v[36:39]
	v_mfma_f32_16x16x32_bf16 v[52:55], v[152:155], v[164:167], v[52:55]
	s_add_u32 m0, s41, 0x2000
	v_mfma_f32_16x16x32_bf16 v[68:71], v[156:159], v[164:167], v[68:71]
	global_load_lds_dwordx4 v223, s[44:45]
	v_mfma_f32_16x16x32_bf16 v[84:87], v[160:163], v[164:167], v[84:87]
	v_mfma_f32_16x16x32_bf16 v[8:11], v[140:143], v[168:171], v[8:11]
	s_add_u32 m0, s41, 0x4000
	v_mfma_f32_16x16x32_bf16 v[24:27], v[144:147], v[168:171], v[24:27]
	global_load_lds_dwordx4 v224, s[44:45]
	v_mfma_f32_16x16x32_bf16 v[40:43], v[148:151], v[168:171], v[40:43]
	v_mfma_f32_16x16x32_bf16 v[56:59], v[152:155], v[168:171], v[56:59]
	s_add_u32 m0, s41, 0x6000
	v_mfma_f32_16x16x32_bf16 v[72:75], v[156:159], v[168:171], v[72:75]
	global_load_lds_dwordx4 v222, s[46:47]
	v_mfma_f32_16x16x32_bf16 v[88:91], v[160:163], v[168:171], v[88:91]
	v_mfma_f32_16x16x32_bf16 v[12:15], v[140:143], v[172:175], v[12:15]
	s_add_u32 m0, s41, 0x8000
	v_mfma_f32_16x16x32_bf16 v[28:31], v[144:147], v[172:175], v[28:31]
	global_load_lds_dwordx4 v223, s[46:47]
	v_mfma_f32_16x16x32_bf16 v[44:47], v[148:151], v[172:175], v[44:47]
	v_mfma_f32_16x16x32_bf16 v[60:63], v[152:155], v[172:175], v[60:63]
	s_add_u32 m0, s41, 0xa000
	v_mfma_f32_16x16x32_bf16 v[76:79], v[156:159], v[172:175], v[76:79]
	global_load_lds_dwordx4 v224, s[46:47]
	v_mfma_f32_16x16x32_bf16 v[92:95], v[160:163], v[172:175], v[92:95]
	v_mfma_f32_16x16x32_bf16 v[16:19], v[140:143], v[176:179], v[16:19]
	s_add_u32 m0, s41, 0xc000
	v_mfma_f32_16x16x32_bf16 v[32:35], v[144:147], v[176:179], v[32:35]
	global_load_lds_dwordx4 v225, s[46:47]
	v_mfma_f32_16x16x32_bf16 v[48:51], v[148:151], v[176:179], v[48:51]
	v_mfma_f32_16x16x32_bf16 v[64:67], v[152:155], v[176:179], v[64:67]
	v_mfma_f32_16x16x32_bf16 v[80:83], v[156:159], v[176:179], v[80:83]
	v_mfma_f32_16x16x32_bf16 v[96:99], v[160:163], v[176:179], v[96:99]

.Lgm_f1_dadv5:
	s_add_u32 s34, s34, 1
	s_add_u32 s31, s31, 1
	s_mov_b32 s4, 0xffff2000
	s_cmp_eq_u32 s40, 0
	s_cselect_b32 s4, 0xe000, s4
	s_cselect_b32 s40, 0xe000, 0
	v_add_u32_e32 v199, s4, v199
	v_add_u32_e32 v200, s4, v200
	v_add_u32_e32 v201, s4, v201
	v_add_u32_e32 v202, s4, v202
	s_cmp_lt_u32 s34, 16
	s_cbranch_scc1 .Lgm_f1_next
	s_and_b32 s6, s35, 31
	s_lshr_b32 s7, s35, 5
	s_mul_i32 s6, s6, 192
	s_lshl_b32 s7, s7, 8
	s_nop 7
	s_mul_i32 s4, s6, 0x2000
	s_lshl_b32 s5, s7, 1
	s_add_u32 s4, s4, s5
	v_add_u32_e32 v197, s4, v205
	ds_write_b32 v203, v4 offset:0
	ds_write_b32 v203, v5 offset:272
	ds_write_b32 v203, v6 offset:544
	ds_write_b32 v203, v7 offset:816
	ds_write_b32 v203, v8 offset:64
	ds_write_b32 v203, v9 offset:336
	ds_write_b32 v203, v10 offset:608
	ds_write_b32 v203, v11 offset:880
	ds_write_b32 v203, v12 offset:128
	ds_write_b32 v203, v13 offset:400
	ds_write_b32 v203, v14 offset:672
	ds_write_b32 v203, v15 offset:944
	ds_write_b32 v203, v16 offset:192
	ds_write_b32 v203, v17 offset:464
	ds_write_b32 v203, v18 offset:736
	ds_write_b32 v203, v19 offset:1008
	s_waitcnt lgkmcnt(0)
	ds_read_b128 v[156:159], v204 offset:0
	ds_read_b128 v[160:163], v204 offset:1088
	ds_read_b128 v[164:167], v204 offset:2176
	ds_read_b128 v[168:171], v204 offset:3264
	s_waitcnt lgkmcnt(3)
	v_max_f32_e32 v156, 0, v156
	v_max_f32_e32 v157, 0, v157
	v_max_f32_e32 v158, 0, v158
	v_max_f32_e32 v159, 0, v159
	v_mul_f32_e32 v156, v156, v156
	v_mul_f32_e32 v157, v157, v157
	v_mul_f32_e32 v158, v158, v158
	v_mul_f32_e32 v159, v159, v159
	v_cvt_pk_bf16_f32 v176, v156, v157
	v_cvt_pk_bf16_f32 v177, v158, v159
	global_store_dwordx2 v197, v[176:177], s[56:57] sc0 sc1
	v_add_u32_e32 v197, 0x8000, v197
	s_waitcnt lgkmcnt(2)
	v_max_f32_e32 v160, 0, v160
	v_max_f32_e32 v161, 0, v161
	v_max_f32_e32 v162, 0, v162
	v_max_f32_e32 v163, 0, v163
	v_mul_f32_e32 v160, v160, v160
	v_mul_f32_e32 v161, v161, v161
	v_mul_f32_e32 v162, v162, v162
	v_mul_f32_e32 v163, v163, v163
	v_cvt_pk_bf16_f32 v178, v160, v161
	v_cvt_pk_bf16_f32 v179, v162, v163
	global_store_dwordx2 v197, v[178:179], s[56:57] sc0 sc1
	v_add_u32_e32 v197, 0x8000, v197
	s_waitcnt lgkmcnt(1)
	v_max_f32_e32 v164, 0, v164
	v_max_f32_e32 v165, 0, v165
	v_max_f32_e32 v166, 0, v166
	v_max_f32_e32 v167, 0, v167
	v_mul_f32_e32 v164, v164, v164
	v_mul_f32_e32 v165, v165, v165
	v_mul_f32_e32 v166, v166, v166
	v_mul_f32_e32 v167, v167, v167
	v_cvt_pk_bf16_f32 v176, v164, v165
	v_cvt_pk_bf16_f32 v177, v166, v167
	global_store_dwordx2 v197, v[176:177], s[56:57] sc0 sc1
	v_add_u32_e32 v197, 0x8000, v197
	s_waitcnt lgkmcnt(0)
	v_max_f32_e32 v168, 0, v168
	v_max_f32_e32 v169, 0, v169
	v_max_f32_e32 v170, 0, v170
	v_max_f32_e32 v171, 0, v171
	v_mul_f32_e32 v168, v168, v168
	v_mul_f32_e32 v169, v169, v169
	v_mul_f32_e32 v170, v170, v170
	v_mul_f32_e32 v171, v171, v171
	v_cvt_pk_bf16_f32 v178, v168, v169
	v_cvt_pk_bf16_f32 v179, v170, v171
	global_store_dwordx2 v197, v[178:179], s[56:57] sc0 sc1
	v_add_u32_e32 v197, 0x8000, v197
	ds_write_b32 v203, v20 offset:0
	ds_write_b32 v203, v21 offset:272
	ds_write_b32 v203, v22 offset:544
	ds_write_b32 v203, v23 offset:816
	ds_write_b32 v203, v24 offset:64
	ds_write_b32 v203, v25 offset:336
	ds_write_b32 v203, v26 offset:608
	ds_write_b32 v203, v27 offset:880
	ds_write_b32 v203, v28 offset:128
	ds_write_b32 v203, v29 offset:400
	ds_write_b32 v203, v30 offset:672
	ds_write_b32 v203, v31 offset:944
	ds_write_b32 v203, v32 offset:192
	ds_write_b32 v203, v33 offset:464
	ds_write_b32 v203, v34 offset:736
	ds_write_b32 v203, v35 offset:1008
	s_waitcnt lgkmcnt(0)
	ds_read_b128 v[156:159], v204 offset:0
	ds_read_b128 v[160:163], v204 offset:1088
	ds_read_b128 v[164:167], v204 offset:2176
	ds_read_b128 v[168:171], v204 offset:3264
	s_waitcnt lgkmcnt(3)
	v_max_f32_e32 v156, 0, v156
	v_max_f32_e32 v157, 0, v157
	v_max_f32_e32 v158, 0, v158
	v_max_f32_e32 v159, 0, v159
	v_mul_f32_e32 v156, v156, v156
	v_mul_f32_e32 v157, v157, v157
	v_mul_f32_e32 v158, v158, v158
	v_mul_f32_e32 v159, v159, v159
	v_cvt_pk_bf16_f32 v176, v156, v157
	v_cvt_pk_bf16_f32 v177, v158, v159
	global_store_dwordx2 v197, v[176:177], s[56:57] sc0 sc1
	v_add_u32_e32 v197, 0x8000, v197
	s_waitcnt lgkmcnt(2)
	v_max_f32_e32 v160, 0, v160
	v_max_f32_e32 v161, 0, v161
	v_max_f32_e32 v162, 0, v162
	v_max_f32_e32 v163, 0, v163
	v_mul_f32_e32 v160, v160, v160
	v_mul_f32_e32 v161, v161, v161
	v_mul_f32_e32 v162, v162, v162
	v_mul_f32_e32 v163, v163, v163
	v_cvt_pk_bf16_f32 v178, v160, v161
	v_cvt_pk_bf16_f32 v179, v162, v163
	global_store_dwordx2 v197, v[178:179], s[56:57] sc0 sc1
	v_add_u32_e32 v197, 0x8000, v197
	s_waitcnt lgkmcnt(1)
	v_max_f32_e32 v164, 0, v164
	v_max_f32_e32 v165, 0, v165
	v_max_f32_e32 v166, 0, v166
	v_max_f32_e32 v167, 0, v167
	v_mul_f32_e32 v164, v164, v164
	v_mul_f32_e32 v165, v165, v165
	v_mul_f32_e32 v166, v166, v166
	v_mul_f32_e32 v167, v167, v167
	v_cvt_pk_bf16_f32 v176, v164, v165
	v_cvt_pk_bf16_f32 v177, v166, v167
	global_store_dwordx2 v197, v[176:177], s[56:57] sc0 sc1
	v_add_u32_e32 v197, 0x8000, v197
	s_waitcnt lgkmcnt(0)
	v_max_f32_e32 v168, 0, v168
	v_max_f32_e32 v169, 0, v169
	v_max_f32_e32 v170, 0, v170
	v_max_f32_e32 v171, 0, v171
	v_mul_f32_e32 v168, v168, v168
	v_mul_f32_e32 v169, v169, v169
	v_mul_f32_e32 v170, v170, v170
	v_mul_f32_e32 v171, v171, v171
	v_cvt_pk_bf16_f32 v178, v168, v169
	v_cvt_pk_bf16_f32 v179, v170, v171
	global_store_dwordx2 v197, v[178:179], s[56:57] sc0 sc1
	v_add_u32_e32 v197, 0x8000, v197
	ds_write_b32 v203, v36 offset:0
	ds_write_b32 v203, v37 offset:272
	ds_write_b32 v203, v38 offset:544
	ds_write_b32 v203, v39 offset:816
	ds_write_b32 v203, v40 offset:64
	ds_write_b32 v203, v41 offset:336
	ds_write_b32 v203, v42 offset:608
	ds_write_b32 v203, v43 offset:880
	ds_write_b32 v203, v44 offset:128
	ds_write_b32 v203, v45 offset:400
	ds_write_b32 v203, v46 offset:672
	ds_write_b32 v203, v47 offset:944
	ds_write_b32 v203, v48 offset:192
	ds_write_b32 v203, v49 offset:464
	ds_write_b32 v203, v50 offset:736
	ds_write_b32 v203, v51 offset:1008
	s_waitcnt lgkmcnt(0)
	ds_read_b128 v[156:159], v204 offset:0
	ds_read_b128 v[160:163], v204 offset:1088
	ds_read_b128 v[164:167], v204 offset:2176
	ds_read_b128 v[168:171], v204 offset:3264
	s_waitcnt lgkmcnt(3)
	v_max_f32_e32 v156, 0, v156
	v_max_f32_e32 v157, 0, v157
	v_max_f32_e32 v158, 0, v158
	v_max_f32_e32 v159, 0, v159
	v_mul_f32_e32 v156, v156, v156
	v_mul_f32_e32 v157, v157, v157
	v_mul_f32_e32 v158, v158, v158
	v_mul_f32_e32 v159, v159, v159
	v_cvt_pk_bf16_f32 v176, v156, v157
	v_cvt_pk_bf16_f32 v177, v158, v159
	global_store_dwordx2 v197, v[176:177], s[56:57] sc0 sc1
	v_add_u32_e32 v197, 0x8000, v197
	s_waitcnt lgkmcnt(2)
	v_max_f32_e32 v160, 0, v160
	v_max_f32_e32 v161, 0, v161
	v_max_f32_e32 v162, 0, v162
	v_max_f32_e32 v163, 0, v163
	v_mul_f32_e32 v160, v160, v160
	v_mul_f32_e32 v161, v161, v161
	v_mul_f32_e32 v162, v162, v162
	v_mul_f32_e32 v163, v163, v163
	v_cvt_pk_bf16_f32 v178, v160, v161
	v_cvt_pk_bf16_f32 v179, v162, v163
	global_store_dwordx2 v197, v[178:179], s[56:57] sc0 sc1
	v_add_u32_e32 v197, 0x8000, v197
	s_waitcnt lgkmcnt(1)
	v_max_f32_e32 v164, 0, v164
	v_max_f32_e32 v165, 0, v165
	v_max_f32_e32 v166, 0, v166
	v_max_f32_e32 v167, 0, v167
	v_mul_f32_e32 v164, v164, v164
	v_mul_f32_e32 v165, v165, v165
	v_mul_f32_e32 v166, v166, v166
	v_mul_f32_e32 v167, v167, v167
	v_cvt_pk_bf16_f32 v176, v164, v165
	v_cvt_pk_bf16_f32 v177, v166, v167
	global_store_dwordx2 v197, v[176:177], s[56:57] sc0 sc1
	v_add_u32_e32 v197, 0x8000, v197
	s_waitcnt lgkmcnt(0)
	v_max_f32_e32 v168, 0, v168
	v_max_f32_e32 v169, 0, v169
	v_max_f32_e32 v170, 0, v170
	v_max_f32_e32 v171, 0, v171
	v_mul_f32_e32 v168, v168, v168
	v_mul_f32_e32 v169, v169, v169
	v_mul_f32_e32 v170, v170, v170
	v_mul_f32_e32 v171, v171, v171
	v_cvt_pk_bf16_f32 v178, v168, v169
	v_cvt_pk_bf16_f32 v179, v170, v171
	global_store_dwordx2 v197, v[178:179], s[56:57] sc0 sc1
	v_add_u32_e32 v197, 0x8000, v197
	ds_write_b32 v203, v52 offset:0
	ds_write_b32 v203, v53 offset:272
	ds_write_b32 v203, v54 offset:544
	ds_write_b32 v203, v55 offset:816
	ds_write_b32 v203, v56 offset:64
	ds_write_b32 v203, v57 offset:336
	ds_write_b32 v203, v58 offset:608
	ds_write_b32 v203, v59 offset:880
	ds_write_b32 v203, v60 offset:128
	ds_write_b32 v203, v61 offset:400
	ds_write_b32 v203, v62 offset:672
	ds_write_b32 v203, v63 offset:944
	ds_write_b32 v203, v64 offset:192
	ds_write_b32 v203, v65 offset:464
	ds_write_b32 v203, v66 offset:736
	ds_write_b32 v203, v67 offset:1008
	s_waitcnt lgkmcnt(0)
	ds_read_b128 v[156:159], v204 offset:0
	ds_read_b128 v[160:163], v204 offset:1088
	ds_read_b128 v[164:167], v204 offset:2176
	ds_read_b128 v[168:171], v204 offset:3264
	s_waitcnt lgkmcnt(3)
	v_max_f32_e32 v156, 0, v156
	v_max_f32_e32 v157, 0, v157
	v_max_f32_e32 v158, 0, v158
	v_max_f32_e32 v159, 0, v159
	v_mul_f32_e32 v156, v156, v156
	v_mul_f32_e32 v157, v157, v157
	v_mul_f32_e32 v158, v158, v158
	v_mul_f32_e32 v159, v159, v159
	v_cvt_pk_bf16_f32 v176, v156, v157
	v_cvt_pk_bf16_f32 v177, v158, v159
	global_store_dwordx2 v197, v[176:177], s[56:57] sc0 sc1
	v_add_u32_e32 v197, 0x8000, v197
	s_waitcnt lgkmcnt(2)
	v_max_f32_e32 v160, 0, v160
	v_max_f32_e32 v161, 0, v161
	v_max_f32_e32 v162, 0, v162
	v_max_f32_e32 v163, 0, v163
	v_mul_f32_e32 v160, v160, v160
	v_mul_f32_e32 v161, v161, v161
	v_mul_f32_e32 v162, v162, v162
	v_mul_f32_e32 v163, v163, v163
	v_cvt_pk_bf16_f32 v178, v160, v161
	v_cvt_pk_bf16_f32 v179, v162, v163
	global_store_dwordx2 v197, v[178:179], s[56:57] sc0 sc1
	v_add_u32_e32 v197, 0x8000, v197
	s_waitcnt lgkmcnt(1)
	v_max_f32_e32 v164, 0, v164
	v_max_f32_e32 v165, 0, v165
	v_max_f32_e32 v166, 0, v166
	v_max_f32_e32 v167, 0, v167
	v_mul_f32_e32 v164, v164, v164
	v_mul_f32_e32 v165, v165, v165
	v_mul_f32_e32 v166, v166, v166
	v_mul_f32_e32 v167, v167, v167
	v_cvt_pk_bf16_f32 v176, v164, v165
	v_cvt_pk_bf16_f32 v177, v166, v167
	global_store_dwordx2 v197, v[176:177], s[56:57] sc0 sc1
	v_add_u32_e32 v197, 0x8000, v197
	s_waitcnt lgkmcnt(0)
	v_max_f32_e32 v168, 0, v168
	v_max_f32_e32 v169, 0, v169
	v_max_f32_e32 v170, 0, v170
	v_max_f32_e32 v171, 0, v171
	v_mul_f32_e32 v168, v168, v168
	v_mul_f32_e32 v169, v169, v169
	v_mul_f32_e32 v170, v170, v170
	v_mul_f32_e32 v171, v171, v171
	v_cvt_pk_bf16_f32 v178, v168, v169
	v_cvt_pk_bf16_f32 v179, v170, v171
	global_store_dwordx2 v197, v[178:179], s[56:57] sc0 sc1
	v_add_u32_e32 v197, 0x8000, v197
	ds_write_b32 v203, v68 offset:0
	ds_write_b32 v203, v69 offset:272
	ds_write_b32 v203, v70 offset:544
	ds_write_b32 v203, v71 offset:816
	ds_write_b32 v203, v72 offset:64
	ds_write_b32 v203, v73 offset:336
	ds_write_b32 v203, v74 offset:608
	ds_write_b32 v203, v75 offset:880
	ds_write_b32 v203, v76 offset:128
	ds_write_b32 v203, v77 offset:400
	ds_write_b32 v203, v78 offset:672
	ds_write_b32 v203, v79 offset:944
	ds_write_b32 v203, v80 offset:192
	ds_write_b32 v203, v81 offset:464
	ds_write_b32 v203, v82 offset:736
	ds_write_b32 v203, v83 offset:1008
	s_waitcnt lgkmcnt(0)
	ds_read_b128 v[156:159], v204 offset:0
	ds_read_b128 v[160:163], v204 offset:1088
	ds_read_b128 v[164:167], v204 offset:2176
	ds_read_b128 v[168:171], v204 offset:3264
	s_waitcnt lgkmcnt(3)
	v_max_f32_e32 v156, 0, v156
	v_max_f32_e32 v157, 0, v157
	v_max_f32_e32 v158, 0, v158
	v_max_f32_e32 v159, 0, v159
	v_mul_f32_e32 v156, v156, v156
	v_mul_f32_e32 v157, v157, v157
	v_mul_f32_e32 v158, v158, v158
	v_mul_f32_e32 v159, v159, v159
	v_cvt_pk_bf16_f32 v176, v156, v157
	v_cvt_pk_bf16_f32 v177, v158, v159
	global_store_dwordx2 v197, v[176:177], s[56:57] sc0 sc1
	v_add_u32_e32 v197, 0x8000, v197
	s_waitcnt lgkmcnt(2)
	v_max_f32_e32 v160, 0, v160
	v_max_f32_e32 v161, 0, v161
	v_max_f32_e32 v162, 0, v162
	v_max_f32_e32 v163, 0, v163
	v_mul_f32_e32 v160, v160, v160
	v_mul_f32_e32 v161, v161, v161
	v_mul_f32_e32 v162, v162, v162
	v_mul_f32_e32 v163, v163, v163
	v_cvt_pk_bf16_f32 v178, v160, v161
	v_cvt_pk_bf16_f32 v179, v162, v163
	global_store_dwordx2 v197, v[178:179], s[56:57] sc0 sc1
	v_add_u32_e32 v197, 0x8000, v197
	s_waitcnt lgkmcnt(1)
	v_max_f32_e32 v164, 0, v164
	v_max_f32_e32 v165, 0, v165
	v_max_f32_e32 v166, 0, v166
	v_max_f32_e32 v167, 0, v167
	v_mul_f32_e32 v164, v164, v164
	v_mul_f32_e32 v165, v165, v165
	v_mul_f32_e32 v166, v166, v166
	v_mul_f32_e32 v167, v167, v167
	v_cvt_pk_bf16_f32 v176, v164, v165
	v_cvt_pk_bf16_f32 v177, v166, v167
	global_store_dwordx2 v197, v[176:177], s[56:57] sc0 sc1
	v_add_u32_e32 v197, 0x8000, v197
	s_waitcnt lgkmcnt(0)
	v_max_f32_e32 v168, 0, v168
	v_max_f32_e32 v169, 0, v169
	v_max_f32_e32 v170, 0, v170
	v_max_f32_e32 v171, 0, v171
	v_mul_f32_e32 v168, v168, v168
	v_mul_f32_e32 v169, v169, v169
	v_mul_f32_e32 v170, v170, v170
	v_mul_f32_e32 v171, v171, v171
	v_cvt_pk_bf16_f32 v178, v168, v169
	v_cvt_pk_bf16_f32 v179, v170, v171
	global_store_dwordx2 v197, v[178:179], s[56:57] sc0 sc1
	v_add_u32_e32 v197, 0x8000, v197
	ds_write_b32 v203, v84 offset:0
	ds_write_b32 v203, v85 offset:272
	ds_write_b32 v203, v86 offset:544
	ds_write_b32 v203, v87 offset:816
	ds_write_b32 v203, v88 offset:64
	ds_write_b32 v203, v89 offset:336
	ds_write_b32 v203, v90 offset:608
	ds_write_b32 v203, v91 offset:880
	ds_write_b32 v203, v92 offset:128
	ds_write_b32 v203, v93 offset:400
	ds_write_b32 v203, v94 offset:672
	ds_write_b32 v203, v95 offset:944
	ds_write_b32 v203, v96 offset:192
	ds_write_b32 v203, v97 offset:464
	ds_write_b32 v203, v98 offset:736
	ds_write_b32 v203, v99 offset:1008
	s_waitcnt lgkmcnt(0)
	ds_read_b128 v[156:159], v204 offset:0
	ds_read_b128 v[160:163], v204 offset:1088
	ds_read_b128 v[164:167], v204 offset:2176
	ds_read_b128 v[168:171], v204 offset:3264
	s_waitcnt lgkmcnt(3)
	v_max_f32_e32 v156, 0, v156
	v_max_f32_e32 v157, 0, v157
	v_max_f32_e32 v158, 0, v158
	v_max_f32_e32 v159, 0, v159
	v_mul_f32_e32 v156, v156, v156
	v_mul_f32_e32 v157, v157, v157
	v_mul_f32_e32 v158, v158, v158
	v_mul_f32_e32 v159, v159, v159
	v_cvt_pk_bf16_f32 v176, v156, v157
	v_cvt_pk_bf16_f32 v177, v158, v159
	global_store_dwordx2 v197, v[176:177], s[56:57] sc0 sc1
	v_add_u32_e32 v197, 0x8000, v197
	s_waitcnt lgkmcnt(2)
	v_max_f32_e32 v160, 0, v160
	v_max_f32_e32 v161, 0, v161
	v_max_f32_e32 v162, 0, v162
	v_max_f32_e32 v163, 0, v163
	v_mul_f32_e32 v160, v160, v160
	v_mul_f32_e32 v161, v161, v161
	v_mul_f32_e32 v162, v162, v162
	v_mul_f32_e32 v163, v163, v163
	v_cvt_pk_bf16_f32 v178, v160, v161
	v_cvt_pk_bf16_f32 v179, v162, v163
	global_store_dwordx2 v197, v[178:179], s[56:57] sc0 sc1
	v_add_u32_e32 v197, 0x8000, v197
	s_waitcnt lgkmcnt(1)
	v_max_f32_e32 v164, 0, v164
	v_max_f32_e32 v165, 0, v165
	v_max_f32_e32 v166, 0, v166
	v_max_f32_e32 v167, 0, v167
	v_mul_f32_e32 v164, v164, v164
	v_mul_f32_e32 v165, v165, v165
	v_mul_f32_e32 v166, v166, v166
	v_mul_f32_e32 v167, v167, v167
	v_cvt_pk_bf16_f32 v176, v164, v165
	v_cvt_pk_bf16_f32 v177, v166, v167
	global_store_dwordx2 v197, v[176:177], s[56:57] sc0 sc1
	v_add_u32_e32 v197, 0x8000, v197
	s_waitcnt lgkmcnt(0)
	v_max_f32_e32 v168, 0, v168
	v_max_f32_e32 v169, 0, v169
	v_max_f32_e32 v170, 0, v170
	v_max_f32_e32 v171, 0, v171
	v_mul_f32_e32 v168, v168, v168
	v_mul_f32_e32 v169, v169, v169
	v_mul_f32_e32 v170, v170, v170
	v_mul_f32_e32 v171, v171, v171
	v_cvt_pk_bf16_f32 v178, v168, v169
	v_cvt_pk_bf16_f32 v179, v170, v171
	global_store_dwordx2 v197, v[178:179], s[56:57] sc0 sc1
	v_add_u32_e32 v197, 0x8000, v197
	v_mov_b32_e32 v4, 0
	v_mov_b32_e32 v5, 0
	v_mov_b32_e32 v6, 0
	v_mov_b32_e32 v7, 0
	v_mov_b32_e32 v8, 0
	v_mov_b32_e32 v9, 0
	v_mov_b32_e32 v10, 0
	v_mov_b32_e32 v11, 0
	v_mov_b32_e32 v12, 0
	v_mov_b32_e32 v13, 0
	v_mov_b32_e32 v14, 0
	v_mov_b32_e32 v15, 0
	v_mov_b32_e32 v16, 0
	v_mov_b32_e32 v17, 0
	v_mov_b32_e32 v18, 0
	v_mov_b32_e32 v19, 0
	v_mov_b32_e32 v20, 0
	v_mov_b32_e32 v21, 0
	v_mov_b32_e32 v22, 0
	v_mov_b32_e32 v23, 0
	v_mov_b32_e32 v24, 0
	v_mov_b32_e32 v25, 0
	v_mov_b32_e32 v26, 0
	v_mov_b32_e32 v27, 0
	v_mov_b32_e32 v28, 0
	v_mov_b32_e32 v29, 0
	v_mov_b32_e32 v30, 0
	v_mov_b32_e32 v31, 0
	v_mov_b32_e32 v32, 0
	v_mov_b32_e32 v33, 0
	v_mov_b32_e32 v34, 0
	v_mov_b32_e32 v35, 0
	v_mov_b32_e32 v36, 0
	v_mov_b32_e32 v37, 0
	v_mov_b32_e32 v38, 0
	v_mov_b32_e32 v39, 0
	v_mov_b32_e32 v40, 0
	v_mov_b32_e32 v41, 0
	v_mov_b32_e32 v42, 0
	v_mov_b32_e32 v43, 0
	v_mov_b32_e32 v44, 0
	v_mov_b32_e32 v45, 0
	v_mov_b32_e32 v46, 0
	v_mov_b32_e32 v47, 0
	v_mov_b32_e32 v48, 0
	v_mov_b32_e32 v49, 0
	v_mov_b32_e32 v50, 0
	v_mov_b32_e32 v51, 0
	v_mov_b32_e32 v52, 0
	v_mov_b32_e32 v53, 0
	v_mov_b32_e32 v54, 0
	v_mov_b32_e32 v55, 0
	v_mov_b32_e32 v56, 0
	v_mov_b32_e32 v57, 0
	v_mov_b32_e32 v58, 0
	v_mov_b32_e32 v59, 0
	v_mov_b32_e32 v60, 0
	v_mov_b32_e32 v61, 0
	v_mov_b32_e32 v62, 0
	v_mov_b32_e32 v63, 0
	v_mov_b32_e32 v64, 0
	v_mov_b32_e32 v65, 0
	v_mov_b32_e32 v66, 0
	v_mov_b32_e32 v67, 0
	v_mov_b32_e32 v68, 0
	v_mov_b32_e32 v69, 0
	v_mov_b32_e32 v70, 0
	v_mov_b32_e32 v71, 0
	v_mov_b32_e32 v72, 0
	v_mov_b32_e32 v73, 0
	v_mov_b32_e32 v74, 0
	v_mov_b32_e32 v75, 0
	v_mov_b32_e32 v76, 0
	v_mov_b32_e32 v77, 0
	v_mov_b32_e32 v78, 0
	v_mov_b32_e32 v79, 0
	v_mov_b32_e32 v80, 0
	v_mov_b32_e32 v81, 0
	v_mov_b32_e32 v82, 0
	v_mov_b32_e32 v83, 0
	v_mov_b32_e32 v84, 0
	v_mov_b32_e32 v85, 0
	v_mov_b32_e32 v86, 0
	v_mov_b32_e32 v87, 0
	v_mov_b32_e32 v88, 0
	v_mov_b32_e32 v89, 0
	v_mov_b32_e32 v90, 0
	v_mov_b32_e32 v91, 0
	v_mov_b32_e32 v92, 0
	v_mov_b32_e32 v93, 0
	v_mov_b32_e32 v94, 0
	v_mov_b32_e32 v95, 0
	v_mov_b32_e32 v96, 0
	v_mov_b32_e32 v97, 0
	v_mov_b32_e32 v98, 0
	v_mov_b32_e32 v99, 0
	s_mov_b32 s34, 0
	s_add_u32 s35, s35, s52
	s_cmp_ge_u32 s31, s30
	s_cbranch_scc1 .Lgm_f1_exit
	s_waitcnt vmcnt(31)
	s_branch .Lgm_f1_loop
.Lgm_f1_next:
	s_waitcnt vmcnt(7)
	s_branch .Lgm_f1_loop
